# phase 0: the 16 single-tile RG-LRU gate-weight transposes are spread over workgroups 0-15 instead of all running on workgroup 0
# baseline (speedup 1.0000x reference)
; DI void phase_convert(const Params& P, LAS unsigned char* lds) {
;     ...
;     for (int hb = 0; hb < 8; ++hb) {
;         conv_T(P.in[17] + hb * 4096, 64, 64, (bf16_t*)(P.ws + W_WA) + hb * 4096, 1 << 30, 0, 0, tile);
;         conv_T(P.in[19] + hb * 4096, 64, 64, (bf16_t*)(P.ws + W_WX) + hb * 4096, 1 << 30, 0, 0, tile);
;     }
.LBB0_208:
	s_mov_b32 s8, 0
	s_mov_b32 s27, 0
	s_branch .LBB0_210

; #define LAS __attribute__((address_space(3)))
; DI int otid() { int t = threadIdx.x; asm volatile("" : "+v"(t)); return t; }
; DI void conv_T(const float* src, int K, int N, bf16_t* dst, int grp, int gstride, int goff, LAS float* tile) {
;     const int tid = otid();
;     const int ntn = (N + 63) / 64, ntk = K / 64, ntile = ntn * ntk;
;     const int kk0 = tid >> 4, n4 = (tid & 15) * 4;
;     f32x4 v[2];
;     int t = blockIdx.x;
;     if (t < ntile) {
;         const int k0 = (t / ntn) * 64, n = (t % ntn) * 64 + n4;
; #pragma unroll
;         for (int p = 0; p < 2; ++p) v[p] = (n < N) ? *(const f32x4*)(src + (size_t)(k0 + kk0 + 32 * p) * N + n) : (f32x4){0.f, 0.f, 0.f, 0.f};
;     }
;     for (; t < ntile; t += gridDim.x) {
; DI void phase_convert(const Params& P, LAS unsigned char* lds) {
;     ...
;     for (int hb = 0; hb < 8; ++hb) {
;         conv_T(P.in[17] + hb * 4096, 64, 64, (bf16_t*)(P.ws + W_WA) + hb * 4096, 1 << 30, 0, 0, tile);
;         conv_T(P.in[19] + hb * 4096, 64, 64, (bf16_t*)(P.ws + W_WX) + hb * 4096, 1 << 30, 0, 0, tile);
;     }
.LBB0_210:
	s_lshl_b32 s92, s8, 12
	v_mov_b32_e32 v10, v163
	s_waitcnt vmcnt(0)
	s_add_i32 s2, s8, 8
	s_cmp_lg_u32 s71, s2
	s_cselect_b64 s[0:1], -1, 0
	s_cmp_eq_u32 s71, s8
	s_cbranch_scc1 .LBB0_218

; DI int otid() { int t = threadIdx.x; asm volatile("" : "+v"(t)); return t; }
; DI unsigned pk2(float lo, float hi) { return f2bf(lo) | (f2bf(hi) << 16); }
; DI void conv_plain(const float* src, bf16_t* dst, size_t n) {
;     const size_t stride = (size_t)gridDim.x * NTHREADS * 8;
;     for (size_t i = ((size_t)blockIdx.x * NTHREADS + otid()) * 8; i < n; i += stride) {
;         const f32x4 a = *(const f32x4*)(src + i), b = *(const f32x4*)(src + i + 4);
;         u32x4 w; w.x = pk2(a[0], a[1]); w.y = pk2(a[2], a[3]); w.z = pk2(b[0], b[1]); w.w = pk2(b[2], b[3]);
;         *(u32x4*)(dst + i) = w;
;     }
; DI void phase_convert(const Params& P, LAS unsigned char* lds) {
;     ...
;     conv_plain(P.in[0], (bf16_t*)(P.ws + WS_XB0), (size_t)T_ * D_);
.LBB0_224:
	s_lshl_b32 s27, s71, 6
	s_load_dword s0, s[90:91], 0x10
	s_waitcnt vmcnt(0)
	v_mov_b32_e32 v4, v163
	v_readlane_b32 s2, v253, 22
	v_readlane_b32 s3, v253, 23
	s_waitcnt lgkmcnt(0)
	s_lshr_b32 s0, s0, 16
	s_cmp_lg_u32 s0, 0
	s_cselect_b64 s[0:1], -1, 0
	v_ashrrev_i32_e32 v5, 31, v4
	s_cmp_lg_u64 s[0:1], 0
	v_lshl_add_u64 v[0:1], v[4:5], 3, s[2:3]
	s_addc_u32 s92, s50, 0
	s_mov_b64 s[2:3], 0x4000000
	s_lshl_b64 s[0:1], s[92:93], 12
	v_cmp_gt_u64_e32 vcc, s[2:3], v[0:1]
	s_and_saveexec_b64 s[2:3], vcc
	s_cbranch_execz .LBB0_227
	v_readlane_b32 s4, v255, 0
	v_readlane_b32 s6, v255, 2
	v_lshlrev_b64 v[2:3], 5, v[4:5]
	v_readlane_b32 s5, v255, 1
	v_readlane_b32 s7, v255, 3
	s_mov_b64 s[8:9], 0
	v_lshl_add_u64 v[2:3], s[4:5], 0, v[2:3]
	s_lshl_b64 s[4:5], s[92:93], 14
	v_lshl_add_u64 v[4:5], v[4:5], 4, s[6:7]
	s_lshl_b64 s[6:7], s[92:93], 13
